# GEMM loops: merged MMA(1,0)+MMA(1,1) into 32-MFMA segments (12 barriers per K-iter instead of 16), no setprio; RET edits
# baseline (speedup 1.0000x reference)
; #define PG8_STAGE(bufoff, gbase, voff) do { _Pragma("unroll") for (int _i = 0; _i < 2; ++_i) \
;         __builtin_amdgcn_global_load_lds((const unsigned*)((const char*)(gbase) + (voff)[_i]), (LAS unsigned*)(lds + (bufoff) + ldsw + _i * 8192), 16, 0, 0); } while (0)
; #define PG8_LDA(dst, b, h) do { _Pragma("unroll") for (int m = 0; m < 4; ++m) _Pragma("unroll") for (int k = 0; k < 2; ++k) dst[m][k] = *(const LAS bf16x8*)(lds + PG8_SA(b, h) + aoff + m * 2048 + k * 1024); } while (0)
; #define PG8_LDB(dst, b, h) do { _Pragma("unroll") for (int n = 0; n < 2; ++n) _Pragma("unroll") for (int k = 0; k < 2; ++k) dst[n][k] = *(const LAS bf16x8*)(lds + PG8_SB(b, h) + boff + n * 2048 + k * 1024); } while (0)
; #define PG8_MMA(ai, bj, At, Bt) do { __builtin_amdgcn_s_setprio(1); _Pragma("unroll") for (int m = 0; m < 4; ++m) _Pragma("unroll") for (int n = 0; n < 2; ++n) _Pragma("unroll") for (int k = 0; k < 2; ++k) \
;         acc[ai][bj][m][n] = __builtin_amdgcn_mfma_f32_16x16x32_bf16(Bt[n][k], At[m][k], acc[ai][bj][m][n], 0, 0, 0); __builtin_amdgcn_s_setprio(0); } while (0)
; #define PG8_WAIT_V(n) asm volatile("s_waitcnt vmcnt(" #n ")" ::: "memory")
; #define PG8_WAIT_L(n) asm volatile("s_waitcnt lgkmcnt(" #n ")" ::: "memory")
; #define PG8_BAR __builtin_amdgcn_s_barrier()
; #define PG8_SCHED __builtin_amdgcn_sched_barrier(0)
; template <class Epi, class Sched>
; __device__ __forceinline__ void gemm_phase(LAS unsigned char* lds, const Gemm g, const Sched& S, const Epi& E) {
;     ...
;             PG8_LDB(B0, 0, 0); PG8_SCHED; PG8_LDA(At, 0, 0); PG8_STAGE(PG8_SA(1, 1), a1 + hstep, voffA);
;             PG8_WAIT_L(8); PG8_BAR; PG8_WAIT_L(0); PG8_MMA(0, 0, At, B0); PG8_BAR; PG8_SCHED;
;             PG8_LDB(B1, 0, 1); PG8_STAGE(PG8_SB(0, 0), b2, voffB);
;             PG8_BAR; PG8_WAIT_L(0); PG8_MMA(0, 1, At, B1); PG8_BAR;
;             PG8_LDA(At, 0, 1); PG8_STAGE(PG8_SA(0, 0), a2, voffA);
;             PG8_BAR; PG8_WAIT_L(0); PG8_MMA(1, 0, At, B0); PG8_BAR; PG8_SCHED;
;             PG8_STAGE(PG8_SB(0, 1), b2 + hstep, voffB);
;             PG8_WAIT_V(6); PG8_BAR; PG8_MMA(1, 1, At, B1); PG8_BAR;
.LBB0_232:
	s_add_i32 s33, s29, 2
	s_add_u32 s30, s26, 0x80
	s_addc_u32 s31, s27, 0
	s_add_i32 s42, 0, 0x10000
	v_add_u32_e32 v140, s42, v191
	ds_read_b128 v[128:131], v140
	ds_read_b128 v[132:135], v140 offset:1024
	ds_read_b128 v[136:139], v140 offset:2048
	ds_read_b128 v[140:143], v140 offset:3072
	s_cmp_eq_u32 s76, s29
	s_cselect_b32 s31, s1, s31
	s_cselect_b32 s30, s0, s30
	s_cselect_b32 s35, s9, s25
	s_cselect_b32 s34, s8, s24
	v_lshl_add_u64 v[176:177], s[26:27], 0, v[194:195]
	s_add_i32 m0, s67, 0xc000
	ds_read_b128 v[144:147], v235
	ds_read_b128 v[148:151], v235 offset:1024
	ds_read_b128 v[152:155], v235 offset:2048
	ds_read_b128 v[156:159], v235 offset:3072
	ds_read_b128 v[160:163], v235 offset:4096
	ds_read_b128 v[164:167], v235 offset:5120
	ds_read_b128 v[168:171], v235 offset:6144
	ds_read_b128 v[172:175], v235 offset:7168
	global_load_lds_dwordx4 v[176:177], off
	v_lshl_add_u64 v[176:177], s[26:27], 0, v[192:193]
	s_add_i32 m0, s67, 0xe000
	s_nop 0
	global_load_lds_dwordx4 v[176:177], off
	s_waitcnt lgkmcnt(8)
	s_barrier
	s_waitcnt lgkmcnt(0)
	s_waitcnt lgkmcnt(0)
	v_mfma_f32_16x16x32_bf16 v[120:123], v[128:131], v[144:147], v[120:123]
	v_mfma_f32_16x16x32_bf16 v[112:115], v[136:139], v[144:147], v[112:115]
	v_mfma_f32_16x16x32_bf16 v[104:107], v[128:131], v[152:155], v[104:107]
	v_mfma_f32_16x16x32_bf16 v[96:99], v[136:139], v[152:155], v[96:99]
	v_mfma_f32_16x16x32_bf16 v[88:91], v[128:131], v[160:163], v[88:91]
	v_mfma_f32_16x16x32_bf16 v[80:83], v[136:139], v[160:163], v[80:83]
	v_mfma_f32_16x16x32_bf16 v[72:75], v[128:131], v[168:171], v[72:75]
	v_mfma_f32_16x16x32_bf16 v[64:67], v[136:139], v[168:171], v[64:67]
	v_mfma_f32_16x16x32_bf16 v[120:123], v[132:135], v[148:151], v[120:123]
	v_mfma_f32_16x16x32_bf16 v[112:115], v[140:143], v[148:151], v[112:115]
	v_mfma_f32_16x16x32_bf16 v[104:107], v[132:135], v[156:159], v[104:107]
	v_mfma_f32_16x16x32_bf16 v[96:99], v[140:143], v[156:159], v[96:99]
	v_mfma_f32_16x16x32_bf16 v[88:91], v[132:135], v[164:167], v[88:91]
	v_mfma_f32_16x16x32_bf16 v[80:83], v[140:143], v[164:167], v[80:83]
	v_mfma_f32_16x16x32_bf16 v[72:75], v[132:135], v[172:175], v[72:75]
	v_mfma_f32_16x16x32_bf16 v[64:67], v[140:143], v[172:175], v[64:67]
	s_barrier
	s_add_i32 s29, 0, 0x14000
	s_add_i32 s42, s42, s66
	v_add_u32_e32 v200, s29, v191
	v_lshl_add_u64 v[204:205], s[34:35], 0, v[188:189]
	s_mov_b32 m0, s42
	ds_read_b128 v[176:179], v200
	ds_read_b128 v[180:183], v200 offset:1024
	ds_read_b128 v[196:199], v200 offset:2048
	ds_read_b128 v[200:203], v200 offset:3072
	global_load_lds_dwordx4 v[204:205], off
	v_lshl_add_u64 v[206:207], s[34:35], 0, v[184:185]
	s_add_i32 m0, s42, 0x2000
	s_nop 0
	global_load_lds_dwordx4 v[206:207], off
	s_waitcnt lgkmcnt(0)
	s_barrier
	s_waitcnt lgkmcnt(0)
	s_waitcnt lgkmcnt(0)
	v_mfma_f32_16x16x32_bf16 v[124:127], v[176:179], v[144:147], v[124:127]
	v_mfma_f32_16x16x32_bf16 v[116:119], v[196:199], v[144:147], v[116:119]
	v_mfma_f32_16x16x32_bf16 v[108:111], v[176:179], v[152:155], v[108:111]
	v_mfma_f32_16x16x32_bf16 v[100:103], v[196:199], v[152:155], v[100:103]
	v_mfma_f32_16x16x32_bf16 v[92:95], v[176:179], v[160:163], v[92:95]
	v_mfma_f32_16x16x32_bf16 v[84:87], v[196:199], v[160:163], v[84:87]
	v_mfma_f32_16x16x32_bf16 v[76:79], v[176:179], v[168:171], v[76:79]
	v_mfma_f32_16x16x32_bf16 v[68:71], v[196:199], v[168:171], v[68:71]
	v_mfma_f32_16x16x32_bf16 v[124:127], v[180:183], v[148:151], v[124:127]
	v_mfma_f32_16x16x32_bf16 v[116:119], v[200:203], v[148:151], v[116:119]
	v_mfma_f32_16x16x32_bf16 v[108:111], v[180:183], v[156:159], v[108:111]
	v_mfma_f32_16x16x32_bf16 v[100:103], v[200:203], v[156:159], v[100:103]
	v_mfma_f32_16x16x32_bf16 v[92:95], v[180:183], v[164:167], v[92:95]
	v_mfma_f32_16x16x32_bf16 v[84:87], v[200:203], v[164:167], v[84:87]
	v_mfma_f32_16x16x32_bf16 v[76:79], v[180:183], v[172:175], v[76:79]
	v_mfma_f32_16x16x32_bf16 v[68:71], v[200:203], v[172:175], v[68:71]
	s_mov_b32 m0, s67
	v_lshl_add_u64 v[208:209], s[30:31], 0, v[188:189]
	s_barrier
	ds_read_b128 v[144:147], v235 offset:16384
	ds_read_b128 v[148:151], v235 offset:17408
	ds_read_b128 v[152:155], v235 offset:18432
	ds_read_b128 v[156:159], v235 offset:19456
	ds_read_b128 v[160:163], v235 offset:20480
	ds_read_b128 v[164:167], v235 offset:21504
	ds_read_b128 v[168:171], v235 offset:22528
	ds_read_b128 v[172:175], v235 offset:23552
	global_load_lds_dwordx4 v[208:209], off
	v_lshl_add_u64 v[210:211], s[30:31], 0, v[184:185]
	s_mov_b32 m0, s68
	s_nop 0
	global_load_lds_dwordx4 v[210:211], off
	s_add_u32 s34, s34, s12
	s_addc_u32 s35, s35, s13
	s_add_i32 s29, s29, s66
	v_lshl_add_u64 v[212:213], s[34:35], 0, v[188:189]
	s_mov_b32 m0, s29
	v_lshl_add_u64 v[214:215], s[34:35], 0, v[184:185]
	global_load_lds_dwordx4 v[212:213], off
	s_add_i32 m0, s29, 0x2000
	s_nop 0
	global_load_lds_dwordx4 v[214:215], off
	s_waitcnt vmcnt(6)
	s_waitcnt lgkmcnt(0)
	s_barrier
; #define PG8_STAGE(bufoff, gbase, voff) do { _Pragma("unroll") for (int _i = 0; _i < 2; ++_i) \
;         __builtin_amdgcn_global_load_lds((const unsigned*)((const char*)(gbase) + (voff)[_i]), (LAS unsigned*)(lds + (bufoff) + ldsw + _i * 8192), 16, 0, 0); } while (0)
; #define PG8_LDA(dst, b, h) do { _Pragma("unroll") for (int m = 0; m < 4; ++m) _Pragma("unroll") for (int k = 0; k < 2; ++k) dst[m][k] = *(const LAS bf16x8*)(lds + PG8_SA(b, h) + aoff + m * 2048 + k * 1024); } while (0)
; #define PG8_LDB(dst, b, h) do { _Pragma("unroll") for (int n = 0; n < 2; ++n) _Pragma("unroll") for (int k = 0; k < 2; ++k) dst[n][k] = *(const LAS bf16x8*)(lds + PG8_SB(b, h) + boff + n * 2048 + k * 1024); } while (0)
; #define PG8_MMA(ai, bj, At, Bt) do { __builtin_amdgcn_s_setprio(1); _Pragma("unroll") for (int m = 0; m < 4; ++m) _Pragma("unroll") for (int n = 0; n < 2; ++n) _Pragma("unroll") for (int k = 0; k < 2; ++k) \
;         acc[ai][bj][m][n] = __builtin_amdgcn_mfma_f32_16x16x32_bf16(Bt[n][k], At[m][k], acc[ai][bj][m][n], 0, 0, 0); __builtin_amdgcn_s_setprio(0); } while (0)
; #define PG8_WAIT_V(n) asm volatile("s_waitcnt vmcnt(" #n ")" ::: "memory")
; #define PG8_WAIT_L(n) asm volatile("s_waitcnt lgkmcnt(" #n ")" ::: "memory")
; #define PG8_BAR __builtin_amdgcn_s_barrier()
; #define PG8_SCHED __builtin_amdgcn_sched_barrier(0)
; template <class Epi, class Sched>
; __device__ __forceinline__ void gemm_phase(LAS unsigned char* lds, const Gemm g, const Sched& S, const Epi& E) {
;     ...
;             PG8_BAR; PG8_WAIT_L(0); PG8_MMA(1, 0, At, B0); PG8_BAR; PG8_SCHED;
;             PG8_STAGE(PG8_SB(0, 1), b2 + hstep, voffB);
;             PG8_WAIT_V(6); PG8_BAR; PG8_MMA(1, 1, At, B1); PG8_BAR;
;             PG8_LDB(B0, 1, 0); PG8_SCHED; PG8_LDA(At, 1, 0); PG8_STAGE(PG8_SA(0, 1), a2 + hstep, voffA);
;             PG8_WAIT_L(8); PG8_BAR; PG8_WAIT_L(0); PG8_MMA(0, 0, At, B0); PG8_BAR; PG8_SCHED;
;             PG8_LDB(B1, 1, 1); PG8_STAGE(PG8_SB(1, 0), b3, voffB);
	s_waitcnt lgkmcnt(0)
	s_waitcnt lgkmcnt(0)
	v_mfma_f32_16x16x32_bf16 v[56:59], v[128:131], v[144:147], v[56:59]
	v_mfma_f32_16x16x32_bf16 v[48:51], v[136:139], v[144:147], v[48:51]
	v_mfma_f32_16x16x32_bf16 v[40:43], v[128:131], v[152:155], v[40:43]
	v_mfma_f32_16x16x32_bf16 v[32:35], v[136:139], v[152:155], v[32:35]
	v_mfma_f32_16x16x32_bf16 v[24:27], v[128:131], v[160:163], v[24:27]
	v_mfma_f32_16x16x32_bf16 v[16:19], v[136:139], v[160:163], v[16:19]
	v_mfma_f32_16x16x32_bf16 v[8:11], v[128:131], v[168:171], v[8:11]
	v_mfma_f32_16x16x32_bf16 v[0:3], v[136:139], v[168:171], v[0:3]
	v_mfma_f32_16x16x32_bf16 v[56:59], v[132:135], v[148:151], v[56:59]
	v_mfma_f32_16x16x32_bf16 v[48:51], v[140:143], v[148:151], v[48:51]
	v_mfma_f32_16x16x32_bf16 v[40:43], v[132:135], v[156:159], v[40:43]
	v_mfma_f32_16x16x32_bf16 v[32:35], v[140:143], v[156:159], v[32:35]
	v_mfma_f32_16x16x32_bf16 v[24:27], v[132:135], v[164:167], v[24:27]
	v_mfma_f32_16x16x32_bf16 v[16:19], v[140:143], v[164:167], v[16:19]
	v_mfma_f32_16x16x32_bf16 v[8:11], v[132:135], v[172:175], v[8:11]
	v_mfma_f32_16x16x32_bf16 v[0:3], v[140:143], v[172:175], v[0:3]
	v_mfma_f32_16x16x32_bf16 v[60:63], v[176:179], v[144:147], v[60:63]
	v_mfma_f32_16x16x32_bf16 v[52:55], v[196:199], v[144:147], v[52:55]
	v_mfma_f32_16x16x32_bf16 v[44:47], v[176:179], v[152:155], v[44:47]
	v_mfma_f32_16x16x32_bf16 v[36:39], v[196:199], v[152:155], v[36:39]
	v_mfma_f32_16x16x32_bf16 v[28:31], v[176:179], v[160:163], v[28:31]
	v_mfma_f32_16x16x32_bf16 v[20:23], v[196:199], v[160:163], v[20:23]
	v_mfma_f32_16x16x32_bf16 v[12:15], v[176:179], v[168:171], v[12:15]
	v_mfma_f32_16x16x32_bf16 v[4:7], v[196:199], v[168:171], v[4:7]
	v_mfma_f32_16x16x32_bf16 v[60:63], v[180:183], v[148:151], v[60:63]
	v_mfma_f32_16x16x32_bf16 v[52:55], v[200:203], v[148:151], v[52:55]
	v_mfma_f32_16x16x32_bf16 v[44:47], v[180:183], v[156:159], v[44:47]
	v_mfma_f32_16x16x32_bf16 v[36:39], v[200:203], v[156:159], v[36:39]
	v_mfma_f32_16x16x32_bf16 v[28:31], v[180:183], v[164:167], v[28:31]
	v_mfma_f32_16x16x32_bf16 v[20:23], v[200:203], v[164:167], v[20:23]
	v_mfma_f32_16x16x32_bf16 v[12:15], v[180:183], v[172:175], v[12:15]
	v_mfma_f32_16x16x32_bf16 v[4:7], v[200:203], v[172:175], v[4:7]
	s_add_i32 s29, 0, 0x18000
	v_add_u32_e32 v140, s29, v191
	s_barrier
	ds_read_b128 v[128:131], v140
	ds_read_b128 v[132:135], v140 offset:1024
	ds_read_b128 v[136:139], v140 offset:2048
	ds_read_b128 v[140:143], v140 offset:3072
	s_add_u32 s30, s30, s12
	s_addc_u32 s31, s31, s13
	s_mov_b32 m0, s69
	v_lshl_add_u64 v[176:177], s[30:31], 0, v[188:189]
	ds_read_b128 v[144:147], v235 offset:32768
	ds_read_b128 v[148:151], v235 offset:33792
	ds_read_b128 v[152:155], v235 offset:34816
	ds_read_b128 v[156:159], v235 offset:35840
	ds_read_b128 v[160:163], v235 offset:36864
	ds_read_b128 v[164:167], v235 offset:37888
	ds_read_b128 v[168:171], v235 offset:38912
	ds_read_b128 v[172:175], v235 offset:39936
	global_load_lds_dwordx4 v[176:177], off
	v_lshl_add_u64 v[176:177], s[30:31], 0, v[184:185]
	s_mov_b32 m0, s70
	s_nop 0
	global_load_lds_dwordx4 v[176:177], off
	s_waitcnt lgkmcnt(8)
	s_barrier
	s_waitcnt lgkmcnt(0)
	s_waitcnt lgkmcnt(0)
	v_mfma_f32_16x16x32_bf16 v[120:123], v[128:131], v[144:147], v[120:123]
	v_mfma_f32_16x16x32_bf16 v[112:115], v[136:139], v[144:147], v[112:115]
	v_mfma_f32_16x16x32_bf16 v[104:107], v[128:131], v[152:155], v[104:107]
	v_mfma_f32_16x16x32_bf16 v[96:99], v[136:139], v[152:155], v[96:99]
	v_mfma_f32_16x16x32_bf16 v[88:91], v[128:131], v[160:163], v[88:91]
	v_mfma_f32_16x16x32_bf16 v[80:83], v[136:139], v[160:163], v[80:83]
	v_mfma_f32_16x16x32_bf16 v[72:75], v[128:131], v[168:171], v[72:75]
	v_mfma_f32_16x16x32_bf16 v[64:67], v[136:139], v[168:171], v[64:67]
	v_mfma_f32_16x16x32_bf16 v[120:123], v[132:135], v[148:151], v[120:123]
	v_mfma_f32_16x16x32_bf16 v[112:115], v[140:143], v[148:151], v[112:115]
	v_mfma_f32_16x16x32_bf16 v[104:107], v[132:135], v[156:159], v[104:107]
	v_mfma_f32_16x16x32_bf16 v[96:99], v[140:143], v[156:159], v[96:99]
	v_mfma_f32_16x16x32_bf16 v[88:91], v[132:135], v[164:167], v[88:91]
	v_mfma_f32_16x16x32_bf16 v[80:83], v[140:143], v[164:167], v[80:83]
	v_mfma_f32_16x16x32_bf16 v[72:75], v[132:135], v[172:175], v[72:75]
	v_mfma_f32_16x16x32_bf16 v[64:67], v[140:143], v[172:175], v[64:67]
	s_barrier
	s_add_i32 s30, 0, 0x1c000
	s_add_i32 s29, s29, s66
	v_add_u32_e32 v200, s30, v191
	v_lshl_add_u64 v[204:205], v[204:205], 0, s[64:65]
	s_mov_b32 m0, s29
	ds_read_b128 v[176:179], v200
	ds_read_b128 v[180:183], v200 offset:1024
	ds_read_b128 v[196:199], v200 offset:2048
	ds_read_b128 v[200:203], v200 offset:3072
	global_load_lds_dwordx4 v[204:205], off
	v_lshl_add_u64 v[204:205], v[206:207], 0, s[64:65]
	s_add_i32 m0, s29, 0x2000
	s_nop 0
	global_load_lds_dwordx4 v[204:205], off
	s_waitcnt lgkmcnt(0)
	s_barrier
; #define PG8_STAGE(bufoff, gbase, voff) do { _Pragma("unroll") for (int _i = 0; _i < 2; ++_i) \
;         __builtin_amdgcn_global_load_lds((const unsigned*)((const char*)(gbase) + (voff)[_i]), (LAS unsigned*)(lds + (bufoff) + ldsw + _i * 8192), 16, 0, 0); } while (0)
; #define PG8_LDA(dst, b, h) do { _Pragma("unroll") for (int m = 0; m < 4; ++m) _Pragma("unroll") for (int k = 0; k < 2; ++k) dst[m][k] = *(const LAS bf16x8*)(lds + PG8_SA(b, h) + aoff + m * 2048 + k * 1024); } while (0)
; #define PG8_MMA(ai, bj, At, Bt) do { __builtin_amdgcn_s_setprio(1); _Pragma("unroll") for (int m = 0; m < 4; ++m) _Pragma("unroll") for (int n = 0; n < 2; ++n) _Pragma("unroll") for (int k = 0; k < 2; ++k) \
;         acc[ai][bj][m][n] = __builtin_amdgcn_mfma_f32_16x16x32_bf16(Bt[n][k], At[m][k], acc[ai][bj][m][n], 0, 0, 0); __builtin_amdgcn_s_setprio(0); } while (0)
; #define PG8_WAIT_V(n) asm volatile("s_waitcnt vmcnt(" #n ")" ::: "memory")
; #define PG8_WAIT_L(n) asm volatile("s_waitcnt lgkmcnt(" #n ")" ::: "memory")
; #define PG8_BAR __builtin_amdgcn_s_barrier()
; #define PG8_SCHED __builtin_amdgcn_sched_barrier(0)
; template <class Epi, class Sched>
; __device__ __forceinline__ void gemm_phase(LAS unsigned char* lds, const Gemm g, const Sched& S, const Epi& E) {
;     ...
;             PG8_BAR; PG8_WAIT_L(0); PG8_MMA(0, 1, At, B1); PG8_BAR;
;             PG8_LDA(At, 1, 1); PG8_STAGE(PG8_SA(1, 0), a3, voffA);
;             PG8_BAR; PG8_WAIT_L(0); PG8_MMA(1, 0, At, B0); PG8_BAR; PG8_SCHED;
;             PG8_STAGE(PG8_SB(1, 1), b3 + hstep, voffB);
;             PG8_WAIT_V(6); PG8_BAR; PG8_MMA(1, 1, At, B1); PG8_BAR;
;         }
	s_waitcnt lgkmcnt(0)
	s_waitcnt lgkmcnt(0)
	v_mfma_f32_16x16x32_bf16 v[124:127], v[176:179], v[144:147], v[124:127]
	v_mfma_f32_16x16x32_bf16 v[116:119], v[196:199], v[144:147], v[116:119]
	v_mfma_f32_16x16x32_bf16 v[108:111], v[176:179], v[152:155], v[108:111]
	v_mfma_f32_16x16x32_bf16 v[100:103], v[196:199], v[152:155], v[100:103]
	v_mfma_f32_16x16x32_bf16 v[92:95], v[176:179], v[160:163], v[92:95]
	v_mfma_f32_16x16x32_bf16 v[84:87], v[196:199], v[160:163], v[84:87]
	v_mfma_f32_16x16x32_bf16 v[76:79], v[176:179], v[168:171], v[76:79]
	v_mfma_f32_16x16x32_bf16 v[68:71], v[196:199], v[168:171], v[68:71]
	v_mfma_f32_16x16x32_bf16 v[124:127], v[180:183], v[148:151], v[124:127]
	v_mfma_f32_16x16x32_bf16 v[116:119], v[200:203], v[148:151], v[116:119]
	v_mfma_f32_16x16x32_bf16 v[108:111], v[180:183], v[156:159], v[108:111]
	v_mfma_f32_16x16x32_bf16 v[100:103], v[200:203], v[156:159], v[100:103]
	v_mfma_f32_16x16x32_bf16 v[92:95], v[180:183], v[164:167], v[92:95]
	v_mfma_f32_16x16x32_bf16 v[84:87], v[200:203], v[164:167], v[84:87]
	v_mfma_f32_16x16x32_bf16 v[76:79], v[180:183], v[172:175], v[76:79]
	v_mfma_f32_16x16x32_bf16 v[68:71], v[200:203], v[172:175], v[68:71]
	s_mov_b32 m0, s18
	v_lshl_add_u64 v[204:205], v[208:209], 0, s[64:65]
	s_barrier
	ds_read_b128 v[144:147], v235 offset:49152
	ds_read_b128 v[148:151], v235 offset:50176
	ds_read_b128 v[152:155], v235 offset:51200
	ds_read_b128 v[156:159], v235 offset:52224
	ds_read_b128 v[160:163], v235 offset:53248
	ds_read_b128 v[164:167], v235 offset:54272
	ds_read_b128 v[168:171], v235 offset:55296
	ds_read_b128 v[172:175], v235 offset:56320
	global_load_lds_dwordx4 v[204:205], off
	v_lshl_add_u64 v[204:205], v[210:211], 0, s[64:65]
	s_mov_b32 m0, s75
	s_nop 0
	global_load_lds_dwordx4 v[204:205], off
	s_add_i32 s29, s30, s66
	v_lshl_add_u64 v[236:237], v[212:213], 0, s[64:65]
	s_mov_b32 m0, s29
	s_nop 0
	global_load_lds_dwordx4 v[236:237], off
	v_lshl_add_u64 v[236:237], v[214:215], 0, s[64:65]
	s_add_i32 m0, s29, 0x2000
	s_nop 0
	global_load_lds_dwordx4 v[236:237], off
	s_waitcnt vmcnt(6)
	s_waitcnt lgkmcnt(0)
	s_barrier
	s_waitcnt lgkmcnt(0)
	s_waitcnt lgkmcnt(0)
	v_mfma_f32_16x16x32_bf16 v[56:59], v[128:131], v[144:147], v[56:59]
	v_mfma_f32_16x16x32_bf16 v[48:51], v[136:139], v[144:147], v[48:51]
	v_mfma_f32_16x16x32_bf16 v[40:43], v[128:131], v[152:155], v[40:43]
	v_mfma_f32_16x16x32_bf16 v[32:35], v[136:139], v[152:155], v[32:35]
	v_mfma_f32_16x16x32_bf16 v[24:27], v[128:131], v[160:163], v[24:27]
	v_mfma_f32_16x16x32_bf16 v[16:19], v[136:139], v[160:163], v[16:19]
	v_mfma_f32_16x16x32_bf16 v[8:11], v[128:131], v[168:171], v[8:11]
	v_mfma_f32_16x16x32_bf16 v[0:3], v[136:139], v[168:171], v[0:3]
	v_mfma_f32_16x16x32_bf16 v[56:59], v[132:135], v[148:151], v[56:59]
	v_mfma_f32_16x16x32_bf16 v[48:51], v[140:143], v[148:151], v[48:51]
	v_mfma_f32_16x16x32_bf16 v[40:43], v[132:135], v[156:159], v[40:43]
	v_mfma_f32_16x16x32_bf16 v[32:35], v[140:143], v[156:159], v[32:35]
	v_mfma_f32_16x16x32_bf16 v[24:27], v[132:135], v[164:167], v[24:27]
	v_mfma_f32_16x16x32_bf16 v[16:19], v[140:143], v[164:167], v[16:19]
	v_mfma_f32_16x16x32_bf16 v[8:11], v[132:135], v[172:175], v[8:11]
	v_mfma_f32_16x16x32_bf16 v[0:3], v[140:143], v[172:175], v[0:3]
	v_mfma_f32_16x16x32_bf16 v[60:63], v[176:179], v[144:147], v[60:63]
	v_mfma_f32_16x16x32_bf16 v[52:55], v[196:199], v[144:147], v[52:55]
	v_mfma_f32_16x16x32_bf16 v[44:47], v[176:179], v[152:155], v[44:47]
	v_mfma_f32_16x16x32_bf16 v[36:39], v[196:199], v[152:155], v[36:39]
	v_mfma_f32_16x16x32_bf16 v[28:31], v[176:179], v[160:163], v[28:31]
	v_mfma_f32_16x16x32_bf16 v[20:23], v[196:199], v[160:163], v[20:23]
	v_mfma_f32_16x16x32_bf16 v[12:15], v[176:179], v[168:171], v[12:15]
	v_mfma_f32_16x16x32_bf16 v[4:7], v[196:199], v[168:171], v[4:7]
	v_mfma_f32_16x16x32_bf16 v[60:63], v[180:183], v[148:151], v[60:63]
	v_mfma_f32_16x16x32_bf16 v[52:55], v[200:203], v[148:151], v[52:55]
	v_mfma_f32_16x16x32_bf16 v[44:47], v[180:183], v[156:159], v[44:47]
	v_mfma_f32_16x16x32_bf16 v[36:39], v[200:203], v[156:159], v[36:39]
	v_mfma_f32_16x16x32_bf16 v[28:31], v[180:183], v[164:167], v[28:31]
	v_mfma_f32_16x16x32_bf16 v[20:23], v[200:203], v[164:167], v[20:23]
	v_mfma_f32_16x16x32_bf16 v[12:15], v[180:183], v[172:175], v[12:15]
	v_mfma_f32_16x16x32_bf16 v[4:7], v[200:203], v[172:175], v[4:7]
	s_add_u32 s24, s24, 0x100
	s_addc_u32 s25, s25, 0
	s_add_u32 s26, s26, 0x100
	s_addc_u32 s27, s27, 0
	s_cmp_ge_i32 s33, s74
	s_mov_b32 s29, s33
	s_barrier
	s_cbranch_scc0 .LBB0_232
	s_mov_b32 s42, s82
	s_branch .LBB0_235

; #define PG8_STAGE(bufoff, gbase, voff) do { _Pragma("unroll") for (int _i = 0; _i < 2; ++_i) \
;         __builtin_amdgcn_global_load_lds((const unsigned*)((const char*)(gbase) + (voff)[_i]), (LAS unsigned*)(lds + (bufoff) + ldsw + _i * 8192), 16, 0, 0); } while (0)
; #define PG8_LDA(dst, b, h) do { _Pragma("unroll") for (int m = 0; m < 4; ++m) _Pragma("unroll") for (int k = 0; k < 2; ++k) dst[m][k] = *(const LAS bf16x8*)(lds + PG8_SA(b, h) + aoff + m * 2048 + k * 1024); } while (0)
; #define PG8_LDB(dst, b, h) do { _Pragma("unroll") for (int n = 0; n < 2; ++n) _Pragma("unroll") for (int k = 0; k < 2; ++k) dst[n][k] = *(const LAS bf16x8*)(lds + PG8_SB(b, h) + boff + n * 2048 + k * 1024); } while (0)
; #define PG8_MMA(ai, bj, At, Bt) do { __builtin_amdgcn_s_setprio(1); _Pragma("unroll") for (int m = 0; m < 4; ++m) _Pragma("unroll") for (int n = 0; n < 2; ++n) _Pragma("unroll") for (int k = 0; k < 2; ++k) \
;         acc[ai][bj][m][n] = __builtin_amdgcn_mfma_f32_16x16x32_bf16(Bt[n][k], At[m][k], acc[ai][bj][m][n], 0, 0, 0); __builtin_amdgcn_s_setprio(0); } while (0)
; #define PG8_WAIT_V(n) asm volatile("s_waitcnt vmcnt(" #n ")" ::: "memory")
; #define PG8_WAIT_L(n) asm volatile("s_waitcnt lgkmcnt(" #n ")" ::: "memory")
; #define PG8_BAR __builtin_amdgcn_s_barrier()
; #define PG8_SCHED __builtin_amdgcn_sched_barrier(0)
; template <class Epi, class Sched>
; __device__ __forceinline__ void gemm_phase(LAS unsigned char* lds, const Gemm g, const Sched& S, const Epi& E) {
;     ...
;             PG8_LDB(B0, 0, 0); PG8_SCHED; PG8_LDA(At, 0, 0); PG8_STAGE(PG8_SA(1, 1), a1 + hstep, voffA);
;             PG8_WAIT_L(8); PG8_BAR; PG8_WAIT_L(0); PG8_MMA(0, 0, At, B0); PG8_BAR; PG8_SCHED;
;             PG8_LDB(B1, 0, 1); PG8_STAGE(PG8_SB(0, 0), b2, voffB);
;             PG8_BAR; PG8_WAIT_L(0); PG8_MMA(0, 1, At, B1); PG8_BAR;
;             PG8_LDA(At, 0, 1); PG8_STAGE(PG8_SA(0, 0), a2, voffA);
;             PG8_BAR; PG8_WAIT_L(0); PG8_MMA(1, 0, At, B0); PG8_BAR; PG8_SCHED;
;             PG8_STAGE(PG8_SB(0, 1), b2 + hstep, voffB);
;             PG8_WAIT_V(6); PG8_BAR; PG8_MMA(1, 1, At, B1); PG8_BAR;
.LBB0_339:
	s_add_i32 s30, s4, 2
	s_add_u32 s28, s0, 0x80
	s_addc_u32 s5, s1, 0
	s_add_i32 s31, 0, 0x10000
	v_add_u32_e32 v140, s31, v214
	ds_read_b128 v[128:131], v140
	ds_read_b128 v[132:135], v140 offset:1024
	ds_read_b128 v[136:139], v140 offset:2048
	ds_read_b128 v[140:143], v140 offset:3072
	s_cmp_eq_u32 s66, s4
	s_cselect_b32 s4, s18, s28
	s_cselect_b32 s5, s19, s5
	s_cselect_b32 s29, s27, s76
	s_cselect_b32 s28, s26, s75
	v_lshl_add_u64 v[176:177], s[0:1], 0, v[200:201]
	s_add_i32 m0, s50, 0xc000
	ds_read_b128 v[144:147], v221
	ds_read_b128 v[148:151], v221 offset:1024
	ds_read_b128 v[152:155], v221 offset:2048
	ds_read_b128 v[156:159], v221 offset:3072
	ds_read_b128 v[160:163], v221 offset:4096
	ds_read_b128 v[164:167], v221 offset:5120
	ds_read_b128 v[168:171], v221 offset:6144
	ds_read_b128 v[172:175], v221 offset:7168
	global_load_lds_dwordx4 v[176:177], off
	v_lshl_add_u64 v[176:177], s[0:1], 0, v[198:199]
	s_add_i32 m0, s50, 0xe000
	s_nop 0
	global_load_lds_dwordx4 v[176:177], off
	s_waitcnt lgkmcnt(8)
	s_barrier
	s_waitcnt lgkmcnt(0)
	s_waitcnt lgkmcnt(0)
	v_mfma_f32_16x16x32_bf16 v[120:123], v[128:131], v[144:147], v[120:123]
	v_mfma_f32_16x16x32_bf16 v[112:115], v[136:139], v[144:147], v[112:115]
	v_mfma_f32_16x16x32_bf16 v[104:107], v[128:131], v[152:155], v[104:107]
	v_mfma_f32_16x16x32_bf16 v[96:99], v[136:139], v[152:155], v[96:99]
	v_mfma_f32_16x16x32_bf16 v[88:91], v[128:131], v[160:163], v[88:91]
	v_mfma_f32_16x16x32_bf16 v[80:83], v[136:139], v[160:163], v[80:83]
	v_mfma_f32_16x16x32_bf16 v[72:75], v[128:131], v[168:171], v[72:75]
	v_mfma_f32_16x16x32_bf16 v[64:67], v[136:139], v[168:171], v[64:67]
	v_mfma_f32_16x16x32_bf16 v[120:123], v[132:135], v[148:151], v[120:123]
	v_mfma_f32_16x16x32_bf16 v[112:115], v[140:143], v[148:151], v[112:115]
	v_mfma_f32_16x16x32_bf16 v[104:107], v[132:135], v[156:159], v[104:107]
	v_mfma_f32_16x16x32_bf16 v[96:99], v[140:143], v[156:159], v[96:99]
	v_mfma_f32_16x16x32_bf16 v[88:91], v[132:135], v[164:167], v[88:91]
	v_mfma_f32_16x16x32_bf16 v[80:83], v[140:143], v[164:167], v[80:83]
	v_mfma_f32_16x16x32_bf16 v[72:75], v[132:135], v[172:175], v[72:75]
	v_mfma_f32_16x16x32_bf16 v[64:67], v[140:143], v[172:175], v[64:67]
	s_barrier
	s_add_i32 s33, 0, 0x14000
	s_add_i32 s31, s31, s34
	v_add_u32_e32 v188, s33, v214
	v_lshl_add_u64 v[206:207], s[28:29], 0, v[192:193]
	s_mov_b32 m0, s31
	ds_read_b128 v[176:179], v188
	ds_read_b128 v[180:183], v188 offset:1024
	ds_read_b128 v[184:187], v188 offset:2048
	ds_read_b128 v[202:205], v188 offset:3072
	global_load_lds_dwordx4 v[206:207], off
	v_lshl_add_u64 v[208:209], s[28:29], 0, v[194:195]
	s_add_i32 m0, s31, 0x2000
	s_nop 0
	global_load_lds_dwordx4 v[208:209], off
	s_waitcnt lgkmcnt(0)
	s_barrier
	s_waitcnt lgkmcnt(0)
	s_waitcnt lgkmcnt(0)
	v_mfma_f32_16x16x32_bf16 v[124:127], v[176:179], v[144:147], v[124:127]
	v_mfma_f32_16x16x32_bf16 v[116:119], v[184:187], v[144:147], v[116:119]
	v_mfma_f32_16x16x32_bf16 v[108:111], v[176:179], v[152:155], v[108:111]
	v_mfma_f32_16x16x32_bf16 v[100:103], v[184:187], v[152:155], v[100:103]
	v_mfma_f32_16x16x32_bf16 v[92:95], v[176:179], v[160:163], v[92:95]
	v_mfma_f32_16x16x32_bf16 v[84:87], v[184:187], v[160:163], v[84:87]
	v_mfma_f32_16x16x32_bf16 v[76:79], v[176:179], v[168:171], v[76:79]
	v_mfma_f32_16x16x32_bf16 v[68:71], v[184:187], v[168:171], v[68:71]
	v_mfma_f32_16x16x32_bf16 v[124:127], v[180:183], v[148:151], v[124:127]
	v_mfma_f32_16x16x32_bf16 v[116:119], v[202:205], v[148:151], v[116:119]
	v_mfma_f32_16x16x32_bf16 v[108:111], v[180:183], v[156:159], v[108:111]
	v_mfma_f32_16x16x32_bf16 v[100:103], v[202:205], v[156:159], v[100:103]
	v_mfma_f32_16x16x32_bf16 v[92:95], v[180:183], v[164:167], v[92:95]
	v_mfma_f32_16x16x32_bf16 v[84:87], v[202:205], v[164:167], v[84:87]
	v_mfma_f32_16x16x32_bf16 v[76:79], v[180:183], v[172:175], v[76:79]
	v_mfma_f32_16x16x32_bf16 v[68:71], v[202:205], v[172:175], v[68:71]
	s_mov_b32 m0, s50
	v_lshl_add_u64 v[210:211], s[4:5], 0, v[192:193]
	s_barrier
	ds_read_b128 v[144:147], v221 offset:16384
	ds_read_b128 v[148:151], v221 offset:17408
	ds_read_b128 v[152:155], v221 offset:18432
	ds_read_b128 v[156:159], v221 offset:19456
	ds_read_b128 v[160:163], v221 offset:20480
	ds_read_b128 v[164:167], v221 offset:21504
	ds_read_b128 v[168:171], v221 offset:22528
	ds_read_b128 v[172:175], v221 offset:23552
	global_load_lds_dwordx4 v[210:211], off
	v_lshl_add_u64 v[212:213], s[4:5], 0, v[194:195]
	s_mov_b32 m0, s51
	s_nop 0
	global_load_lds_dwordx4 v[212:213], off
	s_add_u32 s28, s28, s20
	s_addc_u32 s29, s29, s21
	s_add_i32 s31, s33, s34
	v_lshl_add_u64 v[222:223], s[28:29], 0, v[192:193]
	s_mov_b32 m0, s31
	v_lshl_add_u64 v[224:225], s[28:29], 0, v[194:195]
	global_load_lds_dwordx4 v[222:223], off
	s_add_i32 m0, s31, 0x2000
	s_nop 0
	global_load_lds_dwordx4 v[224:225], off
	s_waitcnt vmcnt(6)
	s_waitcnt lgkmcnt(0)
	s_barrier
; #define PG8_STAGE(bufoff, gbase, voff) do { _Pragma("unroll") for (int _i = 0; _i < 2; ++_i) \
;         __builtin_amdgcn_global_load_lds((const unsigned*)((const char*)(gbase) + (voff)[_i]), (LAS unsigned*)(lds + (bufoff) + ldsw + _i * 8192), 16, 0, 0); } while (0)
; #define PG8_LDA(dst, b, h) do { _Pragma("unroll") for (int m = 0; m < 4; ++m) _Pragma("unroll") for (int k = 0; k < 2; ++k) dst[m][k] = *(const LAS bf16x8*)(lds + PG8_SA(b, h) + aoff + m * 2048 + k * 1024); } while (0)
; #define PG8_LDB(dst, b, h) do { _Pragma("unroll") for (int n = 0; n < 2; ++n) _Pragma("unroll") for (int k = 0; k < 2; ++k) dst[n][k] = *(const LAS bf16x8*)(lds + PG8_SB(b, h) + boff + n * 2048 + k * 1024); } while (0)
; #define PG8_MMA(ai, bj, At, Bt) do { __builtin_amdgcn_s_setprio(1); _Pragma("unroll") for (int m = 0; m < 4; ++m) _Pragma("unroll") for (int n = 0; n < 2; ++n) _Pragma("unroll") for (int k = 0; k < 2; ++k) \
;         acc[ai][bj][m][n] = __builtin_amdgcn_mfma_f32_16x16x32_bf16(Bt[n][k], At[m][k], acc[ai][bj][m][n], 0, 0, 0); __builtin_amdgcn_s_setprio(0); } while (0)
; #define PG8_WAIT_V(n) asm volatile("s_waitcnt vmcnt(" #n ")" ::: "memory")
; #define PG8_WAIT_L(n) asm volatile("s_waitcnt lgkmcnt(" #n ")" ::: "memory")
; #define PG8_BAR __builtin_amdgcn_s_barrier()
; #define PG8_SCHED __builtin_amdgcn_sched_barrier(0)
; template <class Epi, class Sched>
; __device__ __forceinline__ void gemm_phase(LAS unsigned char* lds, const Gemm g, const Sched& S, const Epi& E) {
;     ...
;             PG8_BAR; PG8_WAIT_L(0); PG8_MMA(1, 0, At, B0); PG8_BAR; PG8_SCHED;
;             PG8_STAGE(PG8_SB(0, 1), b2 + hstep, voffB);
;             PG8_WAIT_V(6); PG8_BAR; PG8_MMA(1, 1, At, B1); PG8_BAR;
;             PG8_LDB(B0, 1, 0); PG8_SCHED; PG8_LDA(At, 1, 0); PG8_STAGE(PG8_SA(0, 1), a2 + hstep, voffA);
;             PG8_WAIT_L(8); PG8_BAR; PG8_WAIT_L(0); PG8_MMA(0, 0, At, B0); PG8_BAR; PG8_SCHED;
;             PG8_LDB(B1, 1, 1); PG8_STAGE(PG8_SB(1, 0), b3, voffB);
	s_waitcnt lgkmcnt(0)
	s_waitcnt lgkmcnt(0)
	v_mfma_f32_16x16x32_bf16 v[60:63], v[128:131], v[144:147], v[60:63]
	v_mfma_f32_16x16x32_bf16 v[52:55], v[136:139], v[144:147], v[52:55]
	v_mfma_f32_16x16x32_bf16 v[44:47], v[128:131], v[152:155], v[44:47]
	v_mfma_f32_16x16x32_bf16 v[36:39], v[136:139], v[152:155], v[36:39]
	v_mfma_f32_16x16x32_bf16 v[28:31], v[128:131], v[160:163], v[28:31]
	v_mfma_f32_16x16x32_bf16 v[20:23], v[136:139], v[160:163], v[20:23]
	v_mfma_f32_16x16x32_bf16 v[12:15], v[128:131], v[168:171], v[12:15]
	v_mfma_f32_16x16x32_bf16 v[4:7], v[136:139], v[168:171], v[4:7]
	v_mfma_f32_16x16x32_bf16 v[60:63], v[132:135], v[148:151], v[60:63]
	v_mfma_f32_16x16x32_bf16 v[52:55], v[140:143], v[148:151], v[52:55]
	v_mfma_f32_16x16x32_bf16 v[44:47], v[132:135], v[156:159], v[44:47]
	v_mfma_f32_16x16x32_bf16 v[36:39], v[140:143], v[156:159], v[36:39]
	v_mfma_f32_16x16x32_bf16 v[28:31], v[132:135], v[164:167], v[28:31]
	v_mfma_f32_16x16x32_bf16 v[20:23], v[140:143], v[164:167], v[20:23]
	v_mfma_f32_16x16x32_bf16 v[12:15], v[132:135], v[172:175], v[12:15]
	v_mfma_f32_16x16x32_bf16 v[4:7], v[140:143], v[172:175], v[4:7]
	v_mfma_f32_16x16x32_bf16 v[56:59], v[176:179], v[144:147], v[56:59]
	v_mfma_f32_16x16x32_bf16 v[48:51], v[184:187], v[144:147], v[48:51]
	v_mfma_f32_16x16x32_bf16 v[40:43], v[176:179], v[152:155], v[40:43]
	v_mfma_f32_16x16x32_bf16 v[32:35], v[184:187], v[152:155], v[32:35]
	v_mfma_f32_16x16x32_bf16 v[24:27], v[176:179], v[160:163], v[24:27]
	v_mfma_f32_16x16x32_bf16 v[16:19], v[184:187], v[160:163], v[16:19]
	v_mfma_f32_16x16x32_bf16 v[8:11], v[176:179], v[168:171], v[8:11]
	v_mfma_f32_16x16x32_bf16 v[0:3], v[184:187], v[168:171], v[0:3]
	v_mfma_f32_16x16x32_bf16 v[56:59], v[180:183], v[148:151], v[56:59]
	v_mfma_f32_16x16x32_bf16 v[48:51], v[202:205], v[148:151], v[48:51]
	v_mfma_f32_16x16x32_bf16 v[40:43], v[180:183], v[156:159], v[40:43]
	v_mfma_f32_16x16x32_bf16 v[32:35], v[202:205], v[156:159], v[32:35]
	v_mfma_f32_16x16x32_bf16 v[24:27], v[180:183], v[164:167], v[24:27]
	v_mfma_f32_16x16x32_bf16 v[16:19], v[202:205], v[164:167], v[16:19]
	v_mfma_f32_16x16x32_bf16 v[8:11], v[180:183], v[172:175], v[8:11]
	v_mfma_f32_16x16x32_bf16 v[0:3], v[202:205], v[172:175], v[0:3]
	s_add_i32 s28, 0, 0x18000
	v_add_u32_e32 v140, s28, v214
	s_barrier
	ds_read_b128 v[128:131], v140
	ds_read_b128 v[132:135], v140 offset:1024
	ds_read_b128 v[136:139], v140 offset:2048
	ds_read_b128 v[140:143], v140 offset:3072
	s_add_u32 s4, s4, s20
	s_addc_u32 s5, s5, s21
	s_mov_b32 m0, s60
	v_lshl_add_u64 v[176:177], s[4:5], 0, v[192:193]
	ds_read_b128 v[144:147], v221 offset:32768
	ds_read_b128 v[148:151], v221 offset:33792
	ds_read_b128 v[152:155], v221 offset:34816
	ds_read_b128 v[156:159], v221 offset:35840
	ds_read_b128 v[160:163], v221 offset:36864
	ds_read_b128 v[164:167], v221 offset:37888
	ds_read_b128 v[168:171], v221 offset:38912
	ds_read_b128 v[172:175], v221 offset:39936
	global_load_lds_dwordx4 v[176:177], off
	v_lshl_add_u64 v[176:177], s[4:5], 0, v[194:195]
	s_mov_b32 m0, s61
	s_nop 0
	global_load_lds_dwordx4 v[176:177], off
	s_waitcnt lgkmcnt(8)
	s_barrier
	s_waitcnt lgkmcnt(0)
	s_waitcnt lgkmcnt(0)
	v_mfma_f32_16x16x32_bf16 v[120:123], v[128:131], v[144:147], v[120:123]
	v_mfma_f32_16x16x32_bf16 v[112:115], v[136:139], v[144:147], v[112:115]
	v_mfma_f32_16x16x32_bf16 v[104:107], v[128:131], v[152:155], v[104:107]
	v_mfma_f32_16x16x32_bf16 v[96:99], v[136:139], v[152:155], v[96:99]
	v_mfma_f32_16x16x32_bf16 v[88:91], v[128:131], v[160:163], v[88:91]
	v_mfma_f32_16x16x32_bf16 v[80:83], v[136:139], v[160:163], v[80:83]
	v_mfma_f32_16x16x32_bf16 v[72:75], v[128:131], v[168:171], v[72:75]
	v_mfma_f32_16x16x32_bf16 v[64:67], v[136:139], v[168:171], v[64:67]
	v_mfma_f32_16x16x32_bf16 v[120:123], v[132:135], v[148:151], v[120:123]
	v_mfma_f32_16x16x32_bf16 v[112:115], v[140:143], v[148:151], v[112:115]
	v_mfma_f32_16x16x32_bf16 v[104:107], v[132:135], v[156:159], v[104:107]
	v_mfma_f32_16x16x32_bf16 v[96:99], v[140:143], v[156:159], v[96:99]
	v_mfma_f32_16x16x32_bf16 v[88:91], v[132:135], v[164:167], v[88:91]
	v_mfma_f32_16x16x32_bf16 v[80:83], v[140:143], v[164:167], v[80:83]
	v_mfma_f32_16x16x32_bf16 v[72:75], v[132:135], v[172:175], v[72:75]
	v_mfma_f32_16x16x32_bf16 v[64:67], v[140:143], v[172:175], v[64:67]
	s_barrier
	s_add_i32 s4, 0, 0x1c000
	s_add_i32 s5, s28, s34
	v_add_u32_e32 v188, s4, v214
	v_lshl_add_u64 v[206:207], v[206:207], 0, s[64:65]
	s_mov_b32 m0, s5
	ds_read_b128 v[176:179], v188
	ds_read_b128 v[180:183], v188 offset:1024
	ds_read_b128 v[184:187], v188 offset:2048
	ds_read_b128 v[202:205], v188 offset:3072
	global_load_lds_dwordx4 v[206:207], off
	v_lshl_add_u64 v[206:207], v[208:209], 0, s[64:65]
	s_add_i32 m0, s5, 0x2000
	s_nop 0
	global_load_lds_dwordx4 v[206:207], off
	s_waitcnt lgkmcnt(0)
	s_barrier
; #define PG8_STAGE(bufoff, gbase, voff) do { _Pragma("unroll") for (int _i = 0; _i < 2; ++_i) \
;         __builtin_amdgcn_global_load_lds((const unsigned*)((const char*)(gbase) + (voff)[_i]), (LAS unsigned*)(lds + (bufoff) + ldsw + _i * 8192), 16, 0, 0); } while (0)
; #define PG8_LDA(dst, b, h) do { _Pragma("unroll") for (int m = 0; m < 4; ++m) _Pragma("unroll") for (int k = 0; k < 2; ++k) dst[m][k] = *(const LAS bf16x8*)(lds + PG8_SA(b, h) + aoff + m * 2048 + k * 1024); } while (0)
; #define PG8_MMA(ai, bj, At, Bt) do { __builtin_amdgcn_s_setprio(1); _Pragma("unroll") for (int m = 0; m < 4; ++m) _Pragma("unroll") for (int n = 0; n < 2; ++n) _Pragma("unroll") for (int k = 0; k < 2; ++k) \
;         acc[ai][bj][m][n] = __builtin_amdgcn_mfma_f32_16x16x32_bf16(Bt[n][k], At[m][k], acc[ai][bj][m][n], 0, 0, 0); __builtin_amdgcn_s_setprio(0); } while (0)
; #define PG8_WAIT_V(n) asm volatile("s_waitcnt vmcnt(" #n ")" ::: "memory")
; #define PG8_WAIT_L(n) asm volatile("s_waitcnt lgkmcnt(" #n ")" ::: "memory")
; #define PG8_BAR __builtin_amdgcn_s_barrier()
; #define PG8_SCHED __builtin_amdgcn_sched_barrier(0)
; template <class Epi, class Sched>
; __device__ __forceinline__ void gemm_phase(LAS unsigned char* lds, const Gemm g, const Sched& S, const Epi& E) {
;     ...
;             PG8_BAR; PG8_WAIT_L(0); PG8_MMA(0, 1, At, B1); PG8_BAR;
;             PG8_LDA(At, 1, 1); PG8_STAGE(PG8_SA(1, 0), a3, voffA);
;             PG8_BAR; PG8_WAIT_L(0); PG8_MMA(1, 0, At, B0); PG8_BAR; PG8_SCHED;
;             PG8_STAGE(PG8_SB(1, 1), b3 + hstep, voffB);
;             PG8_WAIT_V(6); PG8_BAR; PG8_MMA(1, 1, At, B1); PG8_BAR;
;         }
;         E(acc, cur, wr, wc, fr, fq, lds, ui);
;         if (!has_next) break;
	s_waitcnt lgkmcnt(0)
	s_waitcnt lgkmcnt(0)
	v_mfma_f32_16x16x32_bf16 v[124:127], v[176:179], v[144:147], v[124:127]
	v_mfma_f32_16x16x32_bf16 v[116:119], v[184:187], v[144:147], v[116:119]
	v_mfma_f32_16x16x32_bf16 v[108:111], v[176:179], v[152:155], v[108:111]
	v_mfma_f32_16x16x32_bf16 v[100:103], v[184:187], v[152:155], v[100:103]
	v_mfma_f32_16x16x32_bf16 v[92:95], v[176:179], v[160:163], v[92:95]
	v_mfma_f32_16x16x32_bf16 v[84:87], v[184:187], v[160:163], v[84:87]
	v_mfma_f32_16x16x32_bf16 v[76:79], v[176:179], v[168:171], v[76:79]
	v_mfma_f32_16x16x32_bf16 v[68:71], v[184:187], v[168:171], v[68:71]
	v_mfma_f32_16x16x32_bf16 v[124:127], v[180:183], v[148:151], v[124:127]
	v_mfma_f32_16x16x32_bf16 v[116:119], v[202:205], v[148:151], v[116:119]
	v_mfma_f32_16x16x32_bf16 v[108:111], v[180:183], v[156:159], v[108:111]
	v_mfma_f32_16x16x32_bf16 v[100:103], v[202:205], v[156:159], v[100:103]
	v_mfma_f32_16x16x32_bf16 v[92:95], v[180:183], v[164:167], v[92:95]
	v_mfma_f32_16x16x32_bf16 v[84:87], v[202:205], v[164:167], v[84:87]
	v_mfma_f32_16x16x32_bf16 v[76:79], v[180:183], v[172:175], v[76:79]
	v_mfma_f32_16x16x32_bf16 v[68:71], v[202:205], v[172:175], v[68:71]
	s_mov_b32 m0, s62
	v_lshl_add_u64 v[206:207], v[210:211], 0, s[64:65]
	s_barrier
	ds_read_b128 v[144:147], v221 offset:49152
	ds_read_b128 v[148:151], v221 offset:50176
	ds_read_b128 v[152:155], v221 offset:51200
	ds_read_b128 v[156:159], v221 offset:52224
	ds_read_b128 v[160:163], v221 offset:53248
	ds_read_b128 v[164:167], v221 offset:54272
	ds_read_b128 v[168:171], v221 offset:55296
	ds_read_b128 v[172:175], v221 offset:56320
	global_load_lds_dwordx4 v[206:207], off
	v_lshl_add_u64 v[206:207], v[212:213], 0, s[64:65]
	s_mov_b32 m0, s63
	s_nop 0
	global_load_lds_dwordx4 v[206:207], off
	s_add_i32 s4, s4, s34
	v_lshl_add_u64 v[236:237], v[222:223], 0, s[64:65]
	s_mov_b32 m0, s4
	s_nop 0
	global_load_lds_dwordx4 v[236:237], off
	v_lshl_add_u64 v[236:237], v[224:225], 0, s[64:65]
	s_add_i32 m0, s4, 0x2000
	s_nop 0
	global_load_lds_dwordx4 v[236:237], off
	s_waitcnt vmcnt(6)
	s_waitcnt lgkmcnt(0)
	s_barrier
	s_waitcnt lgkmcnt(0)
	s_waitcnt lgkmcnt(0)
	v_mfma_f32_16x16x32_bf16 v[60:63], v[128:131], v[144:147], v[60:63]
	v_mfma_f32_16x16x32_bf16 v[52:55], v[136:139], v[144:147], v[52:55]
	v_mfma_f32_16x16x32_bf16 v[44:47], v[128:131], v[152:155], v[44:47]
	v_mfma_f32_16x16x32_bf16 v[36:39], v[136:139], v[152:155], v[36:39]
	v_mfma_f32_16x16x32_bf16 v[28:31], v[128:131], v[160:163], v[28:31]
	v_mfma_f32_16x16x32_bf16 v[20:23], v[136:139], v[160:163], v[20:23]
	v_mfma_f32_16x16x32_bf16 v[12:15], v[128:131], v[168:171], v[12:15]
	v_mfma_f32_16x16x32_bf16 v[4:7], v[136:139], v[168:171], v[4:7]
	v_mfma_f32_16x16x32_bf16 v[60:63], v[132:135], v[148:151], v[60:63]
	v_mfma_f32_16x16x32_bf16 v[52:55], v[140:143], v[148:151], v[52:55]
	v_mfma_f32_16x16x32_bf16 v[44:47], v[132:135], v[156:159], v[44:47]
	v_mfma_f32_16x16x32_bf16 v[36:39], v[140:143], v[156:159], v[36:39]
	v_mfma_f32_16x16x32_bf16 v[28:31], v[132:135], v[164:167], v[28:31]
	v_mfma_f32_16x16x32_bf16 v[20:23], v[140:143], v[164:167], v[20:23]
	v_mfma_f32_16x16x32_bf16 v[12:15], v[132:135], v[172:175], v[12:15]
	v_mfma_f32_16x16x32_bf16 v[4:7], v[140:143], v[172:175], v[4:7]
	v_mfma_f32_16x16x32_bf16 v[56:59], v[176:179], v[144:147], v[56:59]
	v_mfma_f32_16x16x32_bf16 v[48:51], v[184:187], v[144:147], v[48:51]
	v_mfma_f32_16x16x32_bf16 v[40:43], v[176:179], v[152:155], v[40:43]
	v_mfma_f32_16x16x32_bf16 v[32:35], v[184:187], v[152:155], v[32:35]
	v_mfma_f32_16x16x32_bf16 v[24:27], v[176:179], v[160:163], v[24:27]
	v_mfma_f32_16x16x32_bf16 v[16:19], v[184:187], v[160:163], v[16:19]
	v_mfma_f32_16x16x32_bf16 v[8:11], v[176:179], v[168:171], v[8:11]
	v_mfma_f32_16x16x32_bf16 v[0:3], v[184:187], v[168:171], v[0:3]
	v_mfma_f32_16x16x32_bf16 v[56:59], v[180:183], v[148:151], v[56:59]
	v_mfma_f32_16x16x32_bf16 v[48:51], v[202:205], v[148:151], v[48:51]
	v_mfma_f32_16x16x32_bf16 v[40:43], v[180:183], v[156:159], v[40:43]
	v_mfma_f32_16x16x32_bf16 v[32:35], v[202:205], v[156:159], v[32:35]
	v_mfma_f32_16x16x32_bf16 v[24:27], v[180:183], v[164:167], v[24:27]
	v_mfma_f32_16x16x32_bf16 v[16:19], v[202:205], v[164:167], v[16:19]
	v_mfma_f32_16x16x32_bf16 v[8:11], v[180:183], v[172:175], v[8:11]
	v_mfma_f32_16x16x32_bf16 v[0:3], v[202:205], v[172:175], v[0:3]
	s_add_u32 s75, s75, 0x100
	s_addc_u32 s76, s76, 0
	s_add_u32 s0, s0, 0x100
	s_addc_u32 s1, s1, 0
	s_cmp_ge_i32 s30, s13
	s_mov_b32 s4, s30
	s_barrier
	s_cbranch_scc0 .LBB0_339
	s_mov_b32 s33, 0x200000
	s_cmp_lt_i32 s15, 2
	s_cbranch_scc1 .LBB0_345
